# baseline (speedup 1.0000x reference)
; __device__ __forceinline__ int get_tid512() { int t = threadIdx.x; asm volatile("" : "+v"(t)); return t; }
; #define WAIT_V(n) asm volatile("s_waitcnt vmcnt(" #n ")" ::: "memory")
; template <int EPI> ...
;   const int tid = get_tid512(), lane = tid & 63;
;   const int wid = __builtin_amdgcn_readfirstlane(tid >> 6);
;   const int wr = wid >> 2, wc = wid & 3, fr = lane & 15, fq = lane >> 4;
;   const char* Abase = (const char*)(A + (size_t)brow * lda);
;   const char* Bbase = (const char*)(Bt + (size_t)bcol * ldb);
;   const size_t halfA = (size_t)128 * lda * 2, halfB = (size_t)128 * ldb * 2;
;   unsigned soff[2];
; #pragma unroll
;   for (int i = 0; i < 2; ++i) {
;     int R, C;
;     stage_rc2(wid * 1024 + i * 8192 + lane * 16, R, C);
;     soff[i] = (unsigned)(R * lda + C) * 2u;
;   }
;   constexpr int HB = 16384;
;     ...
;   const int lane_off = (fr * 64 + fq * 16) ^ (((fr >> 3) & 1) << 5);
;     ...
;   if (first) {
;     WAIT_V(0);
;     __syncthreads();
;     STAGE(SBo(0, 0), B0p, 0); STAGE(SAo(0, 0), A0p, 0);
;     STAGE(SBo(0, 1), B1p, 0); STAGE(SAo(0, 1), A1p, 0);
;     STAGE(SBo(1, 0), B0p, 1); STAGE(SAo(1, 0), A0p, 1); STAGE(SBo(1, 1), B1p, 1);
;   }
.LBB0_184:
	v_mov_b32_e32 v142, v196
	s_lshl_b32 s22, s22, 8
	v_readfirstlane_b32 s40, v142
	s_ashr_i32 s42, s40, 6
	s_lshl_b32 s37, s42, 10
	s_lshl_b32 s24, s42, 3
	v_lshlrev_b32_e32 v0, 4, v142
	v_and_b32_e32 v2, 32, v142
	s_waitcnt lgkmcnt(0)
	v_bfe_u32 v1, v142, 2, 4
	s_and_b32 s24, s24, 0x1ffff0
	s_add_i32 s38, s37, 0x2000
	s_lshl_b32 s2, s23, 8
	s_ashr_i32 s23, s22, 31
	s_and_b32 s41, s40, 64
	v_bitop3_b32 v0, v0, v2, 48 bitop3:0x6c
	v_or_b32_e32 v3, s24, v1
	s_lshr_b32 s24, s38, 7
	s_ashr_i32 s3, s2, 31
	v_or_b32_e32 v2, s41, v0
	s_and_b32 s24, s24, 0x1ffff0
	s_lshl_b64 s[26:27], s[22:23], 11
	v_lshl_or_b32 v136, v3, 11, v2
	v_or_b32_e32 v3, s24, v1
	s_add_u32 s24, s8, s26
	v_lshl_or_b32 v138, v3, 11, v2
	s_addc_u32 s25, s9, s27
	s_and_b64 vcc, exec, s[6:7]
	s_lshl_b64 s[6:7], s[2:3], 11
	s_cbranch_vccnz .Ltw_186
	s_add_u32 s44, s34, s6
	s_addc_u32 s45, s35, s7
	s_add_u32 s46, s24, 0x40000
	s_addc_u32 s47, s25, 0
	s_add_u32 s48, s44, 0x40000
	s_addc_u32 s49, s45, 0
	s_add_i32 m0, s37, 0x10000
	s_waitcnt vmcnt(0)
	s_waitcnt vmcnt(0)
	s_barrier
	global_load_lds_dwordx4 v136, s[44:45]
	s_add_i32 m0, s37, 0x12000
	v_mov_b32_e32 v137, v199
	global_load_lds_dwordx4 v138, s[44:45]
	s_mov_b32 m0, s37
	v_lshl_add_u64 v[2:3], s[44:45], 0, v[136:137]
	global_load_lds_dwordx4 v136, s[24:25]
	s_mov_b32 m0, s38
	v_mov_b32_e32 v139, v199
	global_load_lds_dwordx4 v138, s[24:25]
	s_add_i32 m0, s37, 0x14000
	v_lshl_add_u64 v[4:5], s[44:45], 0, v[138:139]
	global_load_lds_dwordx4 v136, s[48:49]
	s_add_i32 m0, s37, 0x16000
	v_lshl_add_u64 v[2:3], v[2:3], 0, s[56:57]
	global_load_lds_dwordx4 v138, s[48:49]
	s_add_i32 m0, s37, 0x4000
	v_lshl_add_u64 v[6:7], s[24:25], 0, v[136:137]
	global_load_lds_dwordx4 v136, s[46:47]
	s_add_i32 m0, s37, 0x6000
	v_lshl_add_u64 v[8:9], s[24:25], 0, v[138:139]
	global_load_lds_dwordx4 v138, s[46:47]
	s_add_i32 m0, s37, 0x18000
	s_nop 0
	global_load_lds_dwordx4 v[2:3], off
	v_lshl_add_u64 v[2:3], v[4:5], 0, s[56:57]
	s_add_i32 m0, s37, 0x1a000
	s_nop 0
	global_load_lds_dwordx4 v[2:3], off
	s_add_i32 m0, s37, 0x8000
	v_lshl_add_u64 v[2:3], v[6:7], 0, s[56:57]
	global_load_lds_dwordx4 v[2:3], off
	s_add_i32 m0, s37, 0xa000
	v_lshl_add_u64 v[2:3], v[8:9], 0, s[56:57]
	s_add_u32 s44, s44, 0x40080
	global_load_lds_dwordx4 v[2:3], off
	s_addc_u32 s45, s45, 0
	s_add_i32 m0, s37, 0x1c000
	s_nop 0
	global_load_lds_dwordx4 v136, s[44:45]
	s_add_i32 m0, s37, 0x1e000
	s_nop 0
	global_load_lds_dwordx4 v138, s[44:45]
	s_waitcnt vmcnt(0)
	s_branch .LBB0_186
.Ltw_186:
	s_waitcnt vmcnt(63)

; #define WAIT_V(n) asm volatile("s_waitcnt vmcnt(" #n ")" ::: "memory")
; #define BAR __builtin_amdgcn_s_barrier()
; template <int EPI> ...
;     ...
;   const int lane_off = (fr * 64 + fq * 16) ^ (((fr >> 3) & 1) << 5);
;   const char* aL = shm + wr * 8192 + lane_off;
;   const char* bL = shm + wc * 4096 + lane_off;
;     ...
;   f32x4 acc[2][2][4][2];
; #pragma unroll
;   for (int a_ = 0; a_ < 2; ++a_)
; #pragma unroll
;     for (int b_ = 0; b_ < 2; ++b_)
; #pragma unroll
;       for (int m = 0; m < 4; ++m)
; #pragma unroll
;         for (int n = 0; n < 2; ++n) acc[a_][b_][m][n] = (f32x4){0.f, 0.f, 0.f, 0.f};
;   bf16x8 At[4][2], B0[2][2], B1[2][2];
;   const int nt = K >> 6;
;   const char* A0p = Abase;
;   const char* A1p = Abase + halfA;
;   const char* B0p = Bbase;
;   const char* B1p = Bbase + halfB;
;   if (first) {
;     WAIT_V(0);
;     __syncthreads();
;     STAGE(SBo(0, 0), B0p, 0); STAGE(SAo(0, 0), A0p, 0);
;     STAGE(SBo(0, 1), B1p, 0); STAGE(SAo(0, 1), A1p, 0);
;     STAGE(SBo(1, 0), B0p, 1); STAGE(SAo(1, 0), A0p, 1); STAGE(SBo(1, 1), B1p, 1);
;   }
;   if (wr == 1) BAR;
;   WAIT_V(0); BAR;
;   BAR;
.LBB0_188:
	v_and_b32_e32 v191, 15, v142
	s_and_b32 s23, s42, 3
	v_and_b32_e32 v2, 48, v142
	v_lshlrev_b32_e32 v3, 2, v142
	v_lshlrev_b32_e32 v4, 6, v191
	s_lshl_b32 s42, s42, 14
	v_and_b32_e32 v3, 32, v3
	s_lshl_b32 s43, s39, 13
	s_lshl_b32 s44, s23, 12
	v_or_b32_e32 v5, v4, v2
	s_and_b32 s42, s42, 0xffff8000
	v_bitop3_b32 v2, v4, v3, v2 bitop3:0x36
	v_bitop3_b32 v3, s44, v5, v3 bitop3:0xf6
	v_lshlrev_b32_e32 v1, 11, v1
	s_add_u32 s6, s30, s6
	v_or_b32_e32 v154, 0x10000, v3
	v_or_b32_e32 v150, 0x14000, v3
	v_or_b32_e32 v146, 0x18000, v3
	v_or_b32_e32 v137, 0x1c000, v3
	v_or_b32_e32 v155, 0x10400, v3
	v_or_b32_e32 v156, 0x10800, v3
	v_or_b32_e32 v157, 0x10c00, v3
	v_or_b32_e32 v151, 0x14400, v3
	v_or_b32_e32 v152, 0x14800, v3
	v_or_b32_e32 v153, 0x14c00, v3
	v_or_b32_e32 v147, 0x18400, v3
	s_nop 0
	v_or_b32_e32 v148, 0x18800, v3
	v_or_b32_e32 v149, 0x18c00, v3
	v_or_b32_e32 v143, 0x1c400, v3
	v_or_b32_e32 v144, 0x1c800, v3
	v_or_b32_e32 v145, 0x1cc00, v3
	v_or3_b32 v3, v0, s42, v1
	s_addc_u32 s7, s31, s7
	s_lshl_b32 s42, s38, 4
	s_and_b32 s42, s42, 0xffff8000
	v_or3_b32 v0, v0, s42, v1
	v_add_u32_e32 v198, s41, v3
	v_add_u32_e32 v0, s41, v0
	v_mov_b32_e32 v1, v199
	v_lshl_add_u64 v[128:129], s[6:7], 0, v[198:199]
	v_lshl_add_u64 v[130:131], s[6:7], 0, v[0:1]
	s_add_u32 s6, s8, s26
	s_waitcnt vmcnt(0)
	s_addc_u32 s7, s9, s27
	v_lshl_add_u64 v[134:135], s[6:7], 0, v[0:1]
	v_mov_b32_e32 v0, 0
	v_and_b32_e32 v140, 63, v142
	v_lshrrev_b32_e32 v141, 2, v142
	v_lshl_add_u64 v[132:133], s[6:7], 0, v[198:199]
	s_mov_b32 s26, -2
	s_mov_b64 s[6:7], 0
	v_add_u32_e32 v139, s43, v2
	v_mov_b32_e32 v1, v0
	v_mov_b32_e32 v2, v0
	v_mov_b32_e32 v3, v0
	v_mov_b32_e32 v4, v0
	v_mov_b32_e32 v5, v0
	v_mov_b32_e32 v6, v0
	v_mov_b32_e32 v7, v0
	v_mov_b32_e32 v8, v0
	v_mov_b32_e32 v9, v0
	v_mov_b32_e32 v10, v0
	v_mov_b32_e32 v11, v0
	v_mov_b32_e32 v12, v0
	v_mov_b32_e32 v13, v0
	v_mov_b32_e32 v14, v0
	v_mov_b32_e32 v15, v0
	v_mov_b32_e32 v16, v0
	v_mov_b32_e32 v17, v0
	v_mov_b32_e32 v18, v0
	v_mov_b32_e32 v19, v0
	v_mov_b32_e32 v20, v0
	v_mov_b32_e32 v21, v0
	v_mov_b32_e32 v22, v0
	v_mov_b32_e32 v23, v0
	v_mov_b32_e32 v24, v0
	v_mov_b32_e32 v25, v0
	v_mov_b32_e32 v26, v0
	v_mov_b32_e32 v27, v0
	v_mov_b32_e32 v28, v0
	v_mov_b32_e32 v29, v0
	v_mov_b32_e32 v30, v0
	v_mov_b32_e32 v31, v0
	v_mov_b32_e32 v32, v0
	v_mov_b32_e32 v33, v0
	v_mov_b32_e32 v34, v0
	v_mov_b32_e32 v35, v0
	v_mov_b32_e32 v36, v0
	v_mov_b32_e32 v37, v0
	v_mov_b32_e32 v38, v0
	v_mov_b32_e32 v39, v0
	v_mov_b32_e32 v40, v0
	v_mov_b32_e32 v41, v0
	v_mov_b32_e32 v42, v0
	v_mov_b32_e32 v43, v0
	v_mov_b32_e32 v44, v0
	v_mov_b32_e32 v45, v0
	v_mov_b32_e32 v46, v0
	v_mov_b32_e32 v47, v0
	v_mov_b32_e32 v48, v0
	v_mov_b32_e32 v49, v0
	v_mov_b32_e32 v50, v0
	v_mov_b32_e32 v51, v0
	v_mov_b32_e32 v52, v0
	v_mov_b32_e32 v53, v0
	v_mov_b32_e32 v54, v0
	v_mov_b32_e32 v55, v0
	v_mov_b32_e32 v56, v0
	v_mov_b32_e32 v57, v0
	v_mov_b32_e32 v58, v0
	v_mov_b32_e32 v59, v0
	v_mov_b32_e32 v60, v0
	v_mov_b32_e32 v61, v0
	v_mov_b32_e32 v62, v0
	v_mov_b32_e32 v63, v0
	v_mov_b32_e32 v64, v0
	v_mov_b32_e32 v65, v0
	v_mov_b32_e32 v66, v0
	v_mov_b32_e32 v67, v0
	v_mov_b32_e32 v68, v0
	v_mov_b32_e32 v69, v0
	v_mov_b32_e32 v70, v0
	v_mov_b32_e32 v71, v0
	v_mov_b32_e32 v72, v0
	v_mov_b32_e32 v73, v0
	v_mov_b32_e32 v74, v0
	v_mov_b32_e32 v75, v0
	v_mov_b32_e32 v76, v0
	v_mov_b32_e32 v77, v0
	v_mov_b32_e32 v78, v0
	v_mov_b32_e32 v79, v0
	v_mov_b32_e32 v80, v0
	v_mov_b32_e32 v81, v0
	v_mov_b32_e32 v82, v0
	v_mov_b32_e32 v83, v0
	v_mov_b32_e32 v84, v0
	v_mov_b32_e32 v85, v0
	v_mov_b32_e32 v86, v0
	v_mov_b32_e32 v87, v0
	v_mov_b32_e32 v88, v0
	v_mov_b32_e32 v89, v0
	v_mov_b32_e32 v90, v0
	v_mov_b32_e32 v91, v0
	v_mov_b32_e32 v92, v0
	v_mov_b32_e32 v93, v0
	v_mov_b32_e32 v94, v0
	v_mov_b32_e32 v95, v0
	v_mov_b32_e32 v96, v0
	v_mov_b32_e32 v97, v0
	v_mov_b32_e32 v98, v0
	v_mov_b32_e32 v99, v0
	v_mov_b32_e32 v100, v0
	v_mov_b32_e32 v101, v0
	v_mov_b32_e32 v102, v0
	v_mov_b32_e32 v103, v0
	v_mov_b32_e32 v104, v0
	v_mov_b32_e32 v105, v0
	v_mov_b32_e32 v106, v0
	v_mov_b32_e32 v107, v0
	v_mov_b32_e32 v108, v0
	v_mov_b32_e32 v109, v0
	v_mov_b32_e32 v110, v0
	v_mov_b32_e32 v111, v0
	v_mov_b32_e32 v112, v0
	v_mov_b32_e32 v113, v0
	v_mov_b32_e32 v114, v0
	v_mov_b32_e32 v115, v0
	v_mov_b32_e32 v116, v0
	v_mov_b32_e32 v117, v0
	v_mov_b32_e32 v118, v0
	v_mov_b32_e32 v119, v0
	v_mov_b32_e32 v120, v0
	v_mov_b32_e32 v121, v0
	v_mov_b32_e32 v122, v0
	v_mov_b32_e32 v123, v0
	v_mov_b32_e32 v124, v0
	v_mov_b32_e32 v125, v0
	v_mov_b32_e32 v126, v0
	v_mov_b32_e32 v127, v0
	s_mov_b64 s[0:1], 0x1500100
	s_mov_b64 s[54:55], 0x1540100
	s_mov_b64 s[92:93], 0x1500180
	s_mov_b64 vcc, 0x1540180
	s_barrier
	s_barrier

; __device__ __forceinline__ int get_tid512() { int t = threadIdx.x; asm volatile("" : "+v"(t)); return t; }
; #define WAIT_V(n) asm volatile("s_waitcnt vmcnt(" #n ")" ::: "memory")
; template <int EPI> ...
;   const int tid = get_tid512(), lane = tid & 63;
;   const int wid = __builtin_amdgcn_readfirstlane(tid >> 6);
;   const int wr = wid >> 2, wc = wid & 3, fr = lane & 15, fq = lane >> 4;
;   const char* Abase = (const char*)(A + (size_t)brow * lda);
;   const char* Bbase = (const char*)(Bt + (size_t)bcol * ldb);
;   const size_t halfA = (size_t)128 * lda * 2, halfB = (size_t)128 * ldb * 2;
;   unsigned soff[2];
; #pragma unroll
;   for (int i = 0; i < 2; ++i) {
;     int R, C;
;     stage_rc2(wid * 1024 + i * 8192 + lane * 16, R, C);
;     soff[i] = (unsigned)(R * lda + C) * 2u;
;   }
;   constexpr int HB = 16384;
;     ...
;   const int lane_off = (fr * 64 + fq * 16) ^ (((fr >> 3) & 1) << 5);
;     ...
;   if (first) {
;     WAIT_V(0);
;     __syncthreads();
;     STAGE(SBo(0, 0), B0p, 0); STAGE(SAo(0, 0), A0p, 0);
;     STAGE(SBo(0, 1), B1p, 0); STAGE(SAo(0, 1), A1p, 0);
;     STAGE(SBo(1, 0), B0p, 1); STAGE(SAo(1, 0), A0p, 1); STAGE(SBo(1, 1), B1p, 1);
;   }
.LBB0_519:
	v_mov_b32_e32 v142, v196
	s_lshl_b32 s36, s22, 8
	v_readfirstlane_b32 s42, v142
	s_ashr_i32 s44, s42, 6
	s_lshl_b32 s3, s44, 5
	s_waitcnt lgkmcnt(0)
	v_lshlrev_b32_e32 v1, 4, v142
	v_and_b32_e32 v2, 32, v142
	s_and_b32 s43, s3, 32
	s_lshl_b32 s3, s44, 3
	s_lshl_b32 s38, s44, 10
	v_bfe_u32 v0, v142, 2, 4
	v_bitop3_b32 v1, v1, v2, 48 bitop3:0x6c
	s_and_b32 s3, s3, 0xfffff0
	v_lshrrev_b32_e32 v1, 1, v1
	v_or_b32_e32 v3, s3, v0
	s_add_i32 s39, s38, 0x2000
	v_or_b32_e32 v2, s43, v1
	v_mul_u32_u24_e32 v3, 0xb00, v3
	s_ashr_i32 s47, s39, 7
	v_or_b32_e32 v3, v2, v3
	s_and_b32 s3, s47, 0xfffff0
	v_lshlrev_b32_e32 v136, 1, v3
	v_or_b32_e32 v3, s3, v0
	s_lshl_b32 s2, s40, 8
	v_mul_u32_u24_e32 v3, 0xb00, v3
	s_mul_i32 s45, s22, 0x160000
	v_or_b32_e32 v2, v3, v2
	s_mul_hi_i32 s46, s36, 0x1600
	s_add_u32 s22, s10, s45
	v_lshlrev_b32_e32 v138, 1, v2
	s_addc_u32 s23, s11, s46
	s_mul_i32 s48, s40, 0x160000
	s_and_b64 vcc, exec, s[6:7]
	s_mul_hi_i32 s6, s2, 0x1600
	s_cbranch_vccnz .Ltw_521
	s_add_u32 s40, s30, s48
	s_addc_u32 s41, s31, s6
	s_add_u32 s50, s22, 0xb0000
	s_addc_u32 s51, s23, 0
	s_add_u32 s52, s40, 0xb0000
	s_addc_u32 s53, s41, 0
	s_add_i32 m0, s38, 0x10000
	s_waitcnt vmcnt(0)
	s_waitcnt vmcnt(0)
	s_barrier
	global_load_lds_dwordx4 v136, s[40:41]
	s_add_i32 m0, s38, 0x12000
	v_mov_b32_e32 v137, v199
	global_load_lds_dwordx4 v138, s[40:41]
	s_mov_b32 m0, s38
	v_lshl_add_u64 v[2:3], s[40:41], 0, v[136:137]
	global_load_lds_dwordx4 v136, s[22:23]
	s_mov_b32 m0, s39
	v_mov_b32_e32 v139, v199
	global_load_lds_dwordx4 v138, s[22:23]
	s_add_i32 m0, s38, 0x14000
	v_lshl_add_u64 v[4:5], s[40:41], 0, v[138:139]
	global_load_lds_dwordx4 v136, s[52:53]
	s_add_i32 m0, s38, 0x16000
	v_lshl_add_u64 v[2:3], v[2:3], 0, s[56:57]
	global_load_lds_dwordx4 v138, s[52:53]
	s_add_i32 m0, s38, 0x4000
	v_lshl_add_u64 v[6:7], s[22:23], 0, v[136:137]
	global_load_lds_dwordx4 v136, s[50:51]
	s_add_i32 m0, s38, 0x6000
	v_lshl_add_u64 v[8:9], s[22:23], 0, v[138:139]
	global_load_lds_dwordx4 v138, s[50:51]
	s_add_i32 m0, s38, 0x18000
	s_nop 0
	global_load_lds_dwordx4 v[2:3], off
	v_lshl_add_u64 v[2:3], v[4:5], 0, s[56:57]
	s_add_i32 m0, s38, 0x1a000
	s_nop 0
	global_load_lds_dwordx4 v[2:3], off
	s_add_i32 m0, s38, 0x8000
	v_lshl_add_u64 v[2:3], v[6:7], 0, s[56:57]
	global_load_lds_dwordx4 v[2:3], off
	s_add_i32 m0, s38, 0xa000
	v_lshl_add_u64 v[2:3], v[8:9], 0, s[56:57]
	s_add_u32 s40, s40, 0xb0080
	global_load_lds_dwordx4 v[2:3], off
	s_addc_u32 s41, s41, 0
	s_add_i32 m0, s38, 0x1c000
	s_nop 0
	global_load_lds_dwordx4 v136, s[40:41]
	s_add_i32 m0, s38, 0x1e000
	s_nop 0
	global_load_lds_dwordx4 v138, s[40:41]
	s_waitcnt vmcnt(0)
	s_branch .LBB0_521

; #define WAIT_V(n) asm volatile("s_waitcnt vmcnt(" #n ")" ::: "memory")
; #define BAR __builtin_amdgcn_s_barrier()
; template <int EPI> ...
;     ...
;   const int lane_off = (fr * 64 + fq * 16) ^ (((fr >> 3) & 1) << 5);
;   const char* aL = shm + wr * 8192 + lane_off;
;   const char* bL = shm + wc * 4096 + lane_off;
;     ...
;   f32x4 acc[2][2][4][2];
; #pragma unroll
;   for (int a_ = 0; a_ < 2; ++a_)
; #pragma unroll
;     for (int b_ = 0; b_ < 2; ++b_)
; #pragma unroll
;       for (int m = 0; m < 4; ++m)
; #pragma unroll
;         for (int n = 0; n < 2; ++n) acc[a_][b_][m][n] = (f32x4){0.f, 0.f, 0.f, 0.f};
;   bf16x8 At[4][2], B0[2][2], B1[2][2];
;   const int nt = K >> 6;
;   const char* A0p = Abase;
;   const char* A1p = Abase + halfA;
;   const char* B0p = Bbase;
;   const char* B1p = Bbase + halfB;
;   if (first) {
;     WAIT_V(0);
;     __syncthreads();
;     STAGE(SBo(0, 0), B0p, 0); STAGE(SAo(0, 0), A0p, 0);
;     STAGE(SBo(0, 1), B1p, 0); STAGE(SAo(0, 1), A1p, 0);
;     STAGE(SBo(1, 0), B0p, 1); STAGE(SAo(1, 0), A0p, 1); STAGE(SBo(1, 1), B1p, 1);
;   }
;   if (wr == 1) BAR;
;   WAIT_V(0); BAR;
;   BAR;
.LBB0_523:
	v_and_b32_e32 v191, 15, v142
	s_and_b32 s40, s44, 3
	v_and_b32_e32 v2, 48, v142
	v_lshlrev_b32_e32 v3, 2, v142
	v_lshlrev_b32_e32 v4, 6, v191
	v_and_b32_e32 v3, 32, v3
	s_lshl_b32 s7, s40, 12
	v_or_b32_e32 v5, v4, v2
	s_ashr_i32 s3, s2, 31
	s_lshl_b32 s50, s41, 13
	v_bitop3_b32 v2, v4, v3, v2 bitop3:0x36
	v_bitop3_b32 v3, s7, v5, v3 bitop3:0xf6
	s_lshr_b32 s7, s44, 1
	s_add_u32 s48, s24, s48
	s_addc_u32 s49, s25, s6
	s_lshr_b32 s6, s47, 4
	s_mul_i32 s7, s7, 0xb000
	s_mul_i32 s6, s6, 0xb000
	v_or_b32_e32 v154, 0x10000, v3
	v_or_b32_e32 v150, 0x14000, v3
	v_or_b32_e32 v146, 0x18000, v3
	v_or_b32_e32 v137, 0x1c000, v3
	v_or_b32_e32 v155, 0x10400, v3
	v_or_b32_e32 v156, 0x10800, v3
	v_or_b32_e32 v157, 0x10c00, v3
	v_or_b32_e32 v151, 0x14400, v3
	v_or_b32_e32 v152, 0x14800, v3
	v_or_b32_e32 v153, 0x14c00, v3
	v_or_b32_e32 v147, 0x18400, v3
	s_nop 0
	v_or_b32_e32 v148, 0x18800, v3
	v_or_b32_e32 v149, 0x18c00, v3
	v_or_b32_e32 v139, 0x1c400, v3
	v_or_b32_e32 v143, 0x1c800, v3
	v_or_b32_e32 v144, 0x1cc00, v3
	v_or_b32_e32 v3, s7, v1
	s_movk_i32 s7, 0xb00
	v_or_b32_e32 v1, s6, v1
	v_mad_u32_u24 v3, v0, s7, v3
	v_mad_u32_u24 v0, v0, s7, v1
	s_add_u32 s6, s10, s45
	s_waitcnt vmcnt(0)
	v_add_lshl_u32 v0, v0, s43, 1
	v_mov_b32_e32 v1, v199
	s_addc_u32 s7, s11, s46
	v_add_lshl_u32 v198, v3, s43, 1
	v_lshl_add_u64 v[130:131], s[48:49], 0, v[0:1]
	v_lshl_add_u64 v[134:135], s[6:7], 0, v[0:1]
	v_mov_b32_e32 v0, 0
	v_and_b32_e32 v140, 63, v142
	v_lshrrev_b32_e32 v141, 2, v142
	v_lshl_add_u64 v[128:129], s[48:49], 0, v[198:199]
	v_lshl_add_u64 v[132:133], s[6:7], 0, v[198:199]
	s_mov_b32 s43, -2
	s_mov_b64 s[6:7], 0
	v_add_u32_e32 v145, s50, v2
	v_mov_b32_e32 v1, v0
	v_mov_b32_e32 v2, v0
	v_mov_b32_e32 v3, v0
	v_mov_b32_e32 v4, v0
	v_mov_b32_e32 v5, v0
	v_mov_b32_e32 v6, v0
	v_mov_b32_e32 v7, v0
	v_mov_b32_e32 v8, v0
	v_mov_b32_e32 v9, v0
	v_mov_b32_e32 v10, v0
	v_mov_b32_e32 v11, v0
	v_mov_b32_e32 v12, v0
	v_mov_b32_e32 v13, v0
	v_mov_b32_e32 v14, v0
	v_mov_b32_e32 v15, v0
	v_mov_b32_e32 v16, v0
	v_mov_b32_e32 v17, v0
	v_mov_b32_e32 v18, v0
	v_mov_b32_e32 v19, v0
	v_mov_b32_e32 v20, v0
	v_mov_b32_e32 v21, v0
	v_mov_b32_e32 v22, v0
	v_mov_b32_e32 v23, v0
	v_mov_b32_e32 v24, v0
	v_mov_b32_e32 v25, v0
	v_mov_b32_e32 v26, v0
	v_mov_b32_e32 v27, v0
	v_mov_b32_e32 v28, v0
	v_mov_b32_e32 v29, v0
	v_mov_b32_e32 v30, v0
	v_mov_b32_e32 v31, v0
	v_mov_b32_e32 v32, v0
	v_mov_b32_e32 v33, v0
	v_mov_b32_e32 v34, v0
	v_mov_b32_e32 v35, v0
	v_mov_b32_e32 v36, v0
	v_mov_b32_e32 v37, v0
	v_mov_b32_e32 v38, v0
	v_mov_b32_e32 v39, v0
	v_mov_b32_e32 v40, v0
	v_mov_b32_e32 v41, v0
	v_mov_b32_e32 v42, v0
	v_mov_b32_e32 v43, v0
	v_mov_b32_e32 v44, v0
	v_mov_b32_e32 v45, v0
	v_mov_b32_e32 v46, v0
	v_mov_b32_e32 v47, v0
	v_mov_b32_e32 v48, v0
	v_mov_b32_e32 v49, v0
	v_mov_b32_e32 v50, v0
	v_mov_b32_e32 v51, v0
	v_mov_b32_e32 v52, v0
	v_mov_b32_e32 v53, v0
	v_mov_b32_e32 v54, v0
	v_mov_b32_e32 v55, v0
	v_mov_b32_e32 v56, v0
	v_mov_b32_e32 v57, v0
	v_mov_b32_e32 v58, v0
	v_mov_b32_e32 v59, v0
	v_mov_b32_e32 v60, v0
	v_mov_b32_e32 v61, v0
	v_mov_b32_e32 v62, v0
	v_mov_b32_e32 v63, v0
	v_mov_b32_e32 v64, v0
	v_mov_b32_e32 v65, v0
	v_mov_b32_e32 v66, v0
	v_mov_b32_e32 v67, v0
	v_mov_b32_e32 v68, v0
	v_mov_b32_e32 v69, v0
	v_mov_b32_e32 v70, v0
	v_mov_b32_e32 v71, v0
	v_mov_b32_e32 v72, v0
	v_mov_b32_e32 v73, v0
	v_mov_b32_e32 v74, v0
	v_mov_b32_e32 v75, v0
	v_mov_b32_e32 v76, v0
	v_mov_b32_e32 v77, v0
	v_mov_b32_e32 v78, v0
	v_mov_b32_e32 v79, v0
	v_mov_b32_e32 v80, v0
	v_mov_b32_e32 v81, v0
	v_mov_b32_e32 v82, v0
	v_mov_b32_e32 v83, v0
	v_mov_b32_e32 v84, v0
	v_mov_b32_e32 v85, v0
	v_mov_b32_e32 v86, v0
	v_mov_b32_e32 v87, v0
	v_mov_b32_e32 v88, v0
	v_mov_b32_e32 v89, v0
	v_mov_b32_e32 v90, v0
	v_mov_b32_e32 v91, v0
	v_mov_b32_e32 v92, v0
	v_mov_b32_e32 v93, v0
	v_mov_b32_e32 v94, v0
	v_mov_b32_e32 v95, v0
	v_mov_b32_e32 v96, v0
	v_mov_b32_e32 v97, v0
	v_mov_b32_e32 v98, v0
	v_mov_b32_e32 v99, v0
	v_mov_b32_e32 v100, v0
	v_mov_b32_e32 v101, v0
	v_mov_b32_e32 v102, v0
	v_mov_b32_e32 v103, v0
	v_mov_b32_e32 v104, v0
	v_mov_b32_e32 v105, v0
	v_mov_b32_e32 v106, v0
	v_mov_b32_e32 v107, v0
	v_mov_b32_e32 v108, v0
	v_mov_b32_e32 v109, v0
	v_mov_b32_e32 v110, v0
	v_mov_b32_e32 v111, v0
	v_mov_b32_e32 v112, v0
	v_mov_b32_e32 v113, v0
	v_mov_b32_e32 v114, v0
	v_mov_b32_e32 v115, v0
	v_mov_b32_e32 v116, v0
	v_mov_b32_e32 v117, v0
	v_mov_b32_e32 v118, v0
	v_mov_b32_e32 v119, v0
	v_mov_b32_e32 v120, v0
	v_mov_b32_e32 v121, v0
	v_mov_b32_e32 v122, v0
	v_mov_b32_e32 v123, v0
	v_mov_b32_e32 v124, v0
	v_mov_b32_e32 v125, v0
	v_mov_b32_e32 v126, v0
	v_mov_b32_e32 v127, v0
	s_mov_b64 s[0:1], 0xb00100
	s_mov_b64 s[92:93], 0xbb0100
	s_mov_b64 vcc, 0xb00180
	s_mov_b64 s[68:69], 0xbb0180
	s_barrier
	s_barrier

; __device__ __forceinline__ int get_tid512() { int t = threadIdx.x; asm volatile("" : "+v"(t)); return t; }
; #define WAIT_V(n) asm volatile("s_waitcnt vmcnt(" #n ")" ::: "memory")
; template <int EPI> ...
;   const int tid = get_tid512(), lane = tid & 63;
;   const int wid = __builtin_amdgcn_readfirstlane(tid >> 6);
;   const int wr = wid >> 2, wc = wid & 3, fr = lane & 15, fq = lane >> 4;
;   const char* Abase = (const char*)(A + (size_t)brow * lda);
;   const char* Bbase = (const char*)(Bt + (size_t)bcol * ldb);
;   const size_t halfA = (size_t)128 * lda * 2, halfB = (size_t)128 * ldb * 2;
;   unsigned soff[2];
; #pragma unroll
;   for (int i = 0; i < 2; ++i) {
;     int R, C;
;     stage_rc2(wid * 1024 + i * 8192 + lane * 16, R, C);
;     soff[i] = (unsigned)(R * lda + C) * 2u;
;   }
;   constexpr int HB = 16384;
;     ...
;   const int lane_off = (fr * 64 + fq * 16) ^ (((fr >> 3) & 1) << 5);
;     ...
;   if (first) {
;     WAIT_V(0);
;     __syncthreads();
;     STAGE(SBo(0, 0), B0p, 0); STAGE(SAo(0, 0), A0p, 0);
;     STAGE(SBo(0, 1), B1p, 0); STAGE(SAo(0, 1), A1p, 0);
;     STAGE(SBo(1, 0), B0p, 1); STAGE(SAo(1, 0), A0p, 1); STAGE(SBo(1, 1), B1p, 1);
;   }
.LBB0_617:
	v_mov_b32_e32 v141, v196
	s_lshl_b32 s27, s24, 8
	v_readfirstlane_b32 s40, v141
	s_ashr_i32 s42, s40, 6
	s_lshl_b32 s9, s42, 5
	s_waitcnt lgkmcnt(0)
	v_lshlrev_b32_e32 v1, 4, v141
	v_and_b32_e32 v2, 32, v141
	s_and_b32 s41, s9, 32
	s_lshl_b32 s9, s42, 3
	s_lshl_b32 s29, s42, 10
	v_bfe_u32 v0, v141, 2, 4
	v_bitop3_b32 v1, v1, v2, 48 bitop3:0x6c
	s_and_b32 s9, s9, 0xfffff0
	v_lshrrev_b32_e32 v1, 1, v1
	v_or_b32_e32 v3, s9, v0
	s_add_i32 s37, s29, 0x2000
	v_or_b32_e32 v2, s41, v1
	v_mul_u32_u24_e32 v3, 0xb00, v3
	s_ashr_i32 s45, s37, 7
	v_or_b32_e32 v3, v2, v3
	s_and_b32 s9, s45, 0xfffff0
	v_lshlrev_b32_e32 v132, 1, v3
	v_or_b32_e32 v3, s9, v0
	s_lshl_b32 s8, s38, 8
	v_mul_u32_u24_e32 v3, 0xb00, v3
	s_mul_i32 s43, s24, 0x160000
	v_or_b32_e32 v2, v3, v2
	s_mul_hi_i32 s44, s27, 0x1600
	s_add_u32 s24, s2, s43
	v_lshlrev_b32_e32 v134, 1, v2
	s_addc_u32 s25, s3, s44
	s_mul_i32 s46, s38, 0x160000
	s_and_b64 vcc, exec, s[6:7]
	s_mul_hi_i32 s6, s8, 0x1600
	s_cbranch_vccnz .Ltw_619
	s_add_u32 s38, s34, s46
	s_addc_u32 s39, s35, s6
	s_add_u32 s48, s24, 0xb0000
	s_addc_u32 s49, s25, 0
	s_add_u32 s50, s38, 0xb0000
	s_addc_u32 s51, s39, 0
	s_add_i32 m0, s29, 0x10000
	s_waitcnt vmcnt(0)
	s_waitcnt vmcnt(0)
	s_barrier
	global_load_lds_dwordx4 v132, s[38:39]
	s_add_i32 m0, s29, 0x12000
	v_mov_b32_e32 v133, v199
	global_load_lds_dwordx4 v134, s[38:39]
	s_mov_b32 m0, s29
	v_lshl_add_u64 v[2:3], s[38:39], 0, v[132:133]
	global_load_lds_dwordx4 v132, s[24:25]
	s_mov_b32 m0, s37
	v_mov_b32_e32 v135, v199
	global_load_lds_dwordx4 v134, s[24:25]
	s_add_i32 m0, s29, 0x14000
	v_lshl_add_u64 v[4:5], s[38:39], 0, v[134:135]
	global_load_lds_dwordx4 v132, s[50:51]
	s_add_i32 m0, s29, 0x16000
	v_lshl_add_u64 v[2:3], v[2:3], 0, s[56:57]
	global_load_lds_dwordx4 v134, s[50:51]
	s_add_i32 m0, s29, 0x4000
	v_lshl_add_u64 v[6:7], s[24:25], 0, v[132:133]
	global_load_lds_dwordx4 v132, s[48:49]
	s_add_i32 m0, s29, 0x6000
	v_lshl_add_u64 v[8:9], s[24:25], 0, v[134:135]
	global_load_lds_dwordx4 v134, s[48:49]
	s_add_i32 m0, s29, 0x18000
	s_nop 0
	global_load_lds_dwordx4 v[2:3], off
	v_lshl_add_u64 v[2:3], v[4:5], 0, s[56:57]
	s_add_i32 m0, s29, 0x1a000
	s_nop 0
	global_load_lds_dwordx4 v[2:3], off
	s_add_i32 m0, s29, 0x8000
	v_lshl_add_u64 v[2:3], v[6:7], 0, s[56:57]
	global_load_lds_dwordx4 v[2:3], off
	s_add_i32 m0, s29, 0xa000
	v_lshl_add_u64 v[2:3], v[8:9], 0, s[56:57]
	s_add_u32 s38, s38, 0xb0080
	global_load_lds_dwordx4 v[2:3], off
	s_addc_u32 s39, s39, 0
	s_add_i32 m0, s29, 0x1c000
	s_nop 0
	global_load_lds_dwordx4 v132, s[38:39]
	s_add_i32 m0, s29, 0x1e000
	s_nop 0
	global_load_lds_dwordx4 v134, s[38:39]
	s_waitcnt vmcnt(0)
	s_branch .LBB0_619

; #define WAIT_V(n) asm volatile("s_waitcnt vmcnt(" #n ")" ::: "memory")
; #define BAR __builtin_amdgcn_s_barrier()
; template <int EPI> ...
;     ...
;   const int lane_off = (fr * 64 + fq * 16) ^ (((fr >> 3) & 1) << 5);
;   const char* aL = shm + wr * 8192 + lane_off;
;   const char* bL = shm + wc * 4096 + lane_off;
;     ...
;   f32x4 acc[2][2][4][2];
; #pragma unroll
;   for (int a_ = 0; a_ < 2; ++a_)
; #pragma unroll
;     for (int b_ = 0; b_ < 2; ++b_)
; #pragma unroll
;       for (int m = 0; m < 4; ++m)
; #pragma unroll
;         for (int n = 0; n < 2; ++n) acc[a_][b_][m][n] = (f32x4){0.f, 0.f, 0.f, 0.f};
;   bf16x8 At[4][2], B0[2][2], B1[2][2];
;   const int nt = K >> 6;
;   const char* A0p = Abase;
;   const char* A1p = Abase + halfA;
;   const char* B0p = Bbase;
;   const char* B1p = Bbase + halfB;
;   if (first) {
;     WAIT_V(0);
;     __syncthreads();
;     STAGE(SBo(0, 0), B0p, 0); STAGE(SAo(0, 0), A0p, 0);
;     STAGE(SBo(0, 1), B1p, 0); STAGE(SAo(0, 1), A1p, 0);
;     STAGE(SBo(1, 0), B0p, 1); STAGE(SAo(1, 0), A0p, 1); STAGE(SBo(1, 1), B1p, 1);
;   }
;   if (wr == 1) BAR;
;   WAIT_V(0); BAR;
;   BAR;
.LBB0_621:
	v_and_b32_e32 v234, 15, v141
	s_and_b32 s38, s42, 3
	v_and_b32_e32 v2, 48, v141
	v_lshlrev_b32_e32 v3, 2, v141
	v_lshlrev_b32_e32 v4, 6, v234
	v_and_b32_e32 v3, 32, v3
	s_lshl_b32 s7, s38, 12
	v_or_b32_e32 v5, v4, v2
	s_ashr_i32 s9, s8, 31
	s_lshl_b32 s48, s39, 13
	v_bitop3_b32 v2, v4, v3, v2 bitop3:0x36
	v_bitop3_b32 v3, s7, v5, v3 bitop3:0xf6
	s_lshr_b32 s7, s42, 1
	s_add_u32 s46, s30, s46
	s_addc_u32 s47, s31, s6
	s_lshr_b32 s6, s45, 4
	s_mul_i32 s7, s7, 0xb000
	s_mul_i32 s6, s6, 0xb000
	v_or_b32_e32 v153, 0x10000, v3
	v_or_b32_e32 v149, 0x14000, v3
	v_or_b32_e32 v145, 0x18000, v3
	v_or_b32_e32 v133, 0x1c000, v3
	v_or_b32_e32 v154, 0x10400, v3
	v_or_b32_e32 v155, 0x10800, v3
	v_or_b32_e32 v156, 0x10c00, v3
	v_or_b32_e32 v150, 0x14400, v3
	v_or_b32_e32 v151, 0x14800, v3
	v_or_b32_e32 v152, 0x14c00, v3
	v_or_b32_e32 v146, 0x18400, v3
	v_or_b32_e32 v147, 0x18800, v3
	s_nop 0
	v_or_b32_e32 v148, 0x18c00, v3
	v_or_b32_e32 v135, 0x1c400, v3
	v_or_b32_e32 v142, 0x1c800, v3
	v_or_b32_e32 v143, 0x1cc00, v3
	v_or_b32_e32 v3, s7, v1
	s_movk_i32 s7, 0xb00
	v_or_b32_e32 v1, s6, v1
	v_mad_u32_u24 v3, v0, s7, v3
	v_mad_u32_u24 v0, v0, s7, v1
	s_add_u32 s6, s2, s43
	s_waitcnt vmcnt(0)
	v_add_lshl_u32 v0, v0, s41, 1
	v_mov_b32_e32 v1, v199
	s_addc_u32 s7, s3, s44
	v_add_lshl_u32 v198, v3, s41, 1
	v_lshl_add_u64 v[130:131], s[46:47], 0, v[0:1]
	v_lshl_add_u64 v[138:139], s[6:7], 0, v[0:1]
	v_mov_b32_e32 v0, 0
	v_and_b32_e32 v235, 63, v141
	v_lshrrev_b32_e32 v140, 2, v141
	v_lshl_add_u64 v[128:129], s[46:47], 0, v[198:199]
	v_lshl_add_u64 v[136:137], s[6:7], 0, v[198:199]
	s_mov_b32 s41, -2
	s_mov_b64 s[6:7], 0
	v_add_u32_e32 v144, s48, v2
	v_mov_b32_e32 v1, v0
	v_mov_b32_e32 v2, v0
	v_mov_b32_e32 v3, v0
	v_mov_b32_e32 v4, v0
	v_mov_b32_e32 v5, v0
	v_mov_b32_e32 v6, v0
	v_mov_b32_e32 v7, v0
	v_mov_b32_e32 v8, v0
	v_mov_b32_e32 v9, v0
	v_mov_b32_e32 v10, v0
	v_mov_b32_e32 v11, v0
	v_mov_b32_e32 v12, v0
	v_mov_b32_e32 v13, v0
	v_mov_b32_e32 v14, v0
	v_mov_b32_e32 v15, v0
	v_mov_b32_e32 v16, v0
	v_mov_b32_e32 v17, v0
	v_mov_b32_e32 v18, v0
	v_mov_b32_e32 v19, v0
	v_mov_b32_e32 v20, v0
	v_mov_b32_e32 v21, v0
	v_mov_b32_e32 v22, v0
	v_mov_b32_e32 v23, v0
	v_mov_b32_e32 v24, v0
	v_mov_b32_e32 v25, v0
	v_mov_b32_e32 v26, v0
	v_mov_b32_e32 v27, v0
	v_mov_b32_e32 v28, v0
	v_mov_b32_e32 v29, v0
	v_mov_b32_e32 v30, v0
	v_mov_b32_e32 v31, v0
	v_mov_b32_e32 v32, v0
	v_mov_b32_e32 v33, v0
	v_mov_b32_e32 v34, v0
	v_mov_b32_e32 v35, v0
	v_mov_b32_e32 v36, v0
	v_mov_b32_e32 v37, v0
	v_mov_b32_e32 v38, v0
	v_mov_b32_e32 v39, v0
	v_mov_b32_e32 v40, v0
	v_mov_b32_e32 v41, v0
	v_mov_b32_e32 v42, v0
	v_mov_b32_e32 v43, v0
	v_mov_b32_e32 v44, v0
	v_mov_b32_e32 v45, v0
	v_mov_b32_e32 v46, v0
	v_mov_b32_e32 v47, v0
	v_mov_b32_e32 v48, v0
	v_mov_b32_e32 v49, v0
	v_mov_b32_e32 v50, v0
	v_mov_b32_e32 v51, v0
	v_mov_b32_e32 v52, v0
	v_mov_b32_e32 v53, v0
	v_mov_b32_e32 v54, v0
	v_mov_b32_e32 v55, v0
	v_mov_b32_e32 v56, v0
	v_mov_b32_e32 v57, v0
	v_mov_b32_e32 v58, v0
	v_mov_b32_e32 v59, v0
	v_mov_b32_e32 v60, v0
	v_mov_b32_e32 v61, v0
	v_mov_b32_e32 v62, v0
	v_mov_b32_e32 v63, v0
	v_mov_b32_e32 v64, v0
	v_mov_b32_e32 v65, v0
	v_mov_b32_e32 v66, v0
	v_mov_b32_e32 v67, v0
	v_mov_b32_e32 v68, v0
	v_mov_b32_e32 v69, v0
	v_mov_b32_e32 v70, v0
	v_mov_b32_e32 v71, v0
	v_mov_b32_e32 v72, v0
	v_mov_b32_e32 v73, v0
	v_mov_b32_e32 v74, v0
	v_mov_b32_e32 v75, v0
	v_mov_b32_e32 v76, v0
	v_mov_b32_e32 v77, v0
	v_mov_b32_e32 v78, v0
	v_mov_b32_e32 v79, v0
	v_mov_b32_e32 v80, v0
	v_mov_b32_e32 v81, v0
	v_mov_b32_e32 v82, v0
	v_mov_b32_e32 v83, v0
	v_mov_b32_e32 v84, v0
	v_mov_b32_e32 v85, v0
	v_mov_b32_e32 v86, v0
	v_mov_b32_e32 v87, v0
	v_mov_b32_e32 v88, v0
	v_mov_b32_e32 v89, v0
	v_mov_b32_e32 v90, v0
	v_mov_b32_e32 v91, v0
	v_mov_b32_e32 v92, v0
	v_mov_b32_e32 v93, v0
	v_mov_b32_e32 v94, v0
	v_mov_b32_e32 v95, v0
	v_mov_b32_e32 v96, v0
	v_mov_b32_e32 v97, v0
	v_mov_b32_e32 v98, v0
	v_mov_b32_e32 v99, v0
	v_mov_b32_e32 v100, v0
	v_mov_b32_e32 v101, v0
	v_mov_b32_e32 v102, v0
	v_mov_b32_e32 v103, v0
	v_mov_b32_e32 v104, v0
	v_mov_b32_e32 v105, v0
	v_mov_b32_e32 v106, v0
	v_mov_b32_e32 v107, v0
	v_mov_b32_e32 v108, v0
	v_mov_b32_e32 v109, v0
	v_mov_b32_e32 v110, v0
	v_mov_b32_e32 v111, v0
	v_mov_b32_e32 v112, v0
	v_mov_b32_e32 v113, v0
	v_mov_b32_e32 v114, v0
	v_mov_b32_e32 v115, v0
	v_mov_b32_e32 v116, v0
	v_mov_b32_e32 v117, v0
	v_mov_b32_e32 v118, v0
	v_mov_b32_e32 v119, v0
	v_mov_b32_e32 v120, v0
	v_mov_b32_e32 v121, v0
	v_mov_b32_e32 v122, v0
	v_mov_b32_e32 v123, v0
	v_mov_b32_e32 v124, v0
	v_mov_b32_e32 v125, v0
	v_mov_b32_e32 v126, v0
	v_mov_b32_e32 v127, v0
	s_barrier
	s_barrier
